# speedup vs baseline: 1.0109x; 1.0109x over previous
; __device__ __forceinline__ int crow(int r, int hi) { return (r & 3) + 8 * (r >> 2) + 4 * hi; }
; template <int DQK>
; __device__ __forceinline__ void qkt(f32x16& p0, f32x16& p1, const bf16* Ks, const bf16x8* qr, int r32, int hi, int k0, int L) {
;   p0 = f32x16{}; p1 = f32x16{};
; #pragma unroll
;   for (int d0 = 0; d0 < DQK / 16; ++d0) { int cb = (d0 * 16 + hi * 8) * 2;
;     bf16x8 b0 = *reinterpret_cast<const bf16x8*>((const char*)Ks + KSWZ(r32, cb));
;     bf16x8 b1 = *reinterpret_cast<const bf16x8*>((const char*)Ks + KSWZ(32 + r32, cb));
;     p0 = __builtin_amdgcn_mfma_f32_32x32x16_bf16(b0, qr[d0], p0, 0, 0, 0);
;     p1 = __builtin_amdgcn_mfma_f32_32x32x16_bf16(b1, qr[d0], p1, 0, 0, 0); }
;   if (k0 + KVBLK > L) {
; #pragma unroll
;     for (int r = 0; r < 16; ++r) { const int key = k0 + crow(r, hi);
;       if (key >= L) p0[r] = -1e30f;
;       if (key + 32 >= L) p1[r] = -1e30f; }
;   }
.LBB0_832:
	s_and_saveexec_b64 s[2:3], s[8:9]
	s_cbranch_execz .LBB0_838
	ds_read_b128 v[222:225], v167 offset:49152
	ds_read_b128 v[226:229], v168 offset:49152
	ds_read_b128 v[230:233], v167 offset:57344
	ds_read_b128 v[234:237], v168 offset:57344
	ds_read_b128 v[238:241], v169 offset:49152
	ds_read_b128 v[242:245], v169 offset:57344
	ds_read_b128 v[246:249], v171 offset:49152
	ds_read_b128 v[250:253], v171 offset:57344
	s_add_i32 s6, s78, 64
	s_cmp_le_u32 s6, s79
	s_waitcnt lgkmcnt(7)
	v_mfma_f32_32x32x16_bf16 v[66:81], v[222:225], v[98:101], 0
	s_waitcnt lgkmcnt(6)
	v_mfma_f32_32x32x16_bf16 v[66:81], v[226:229], v[102:105], v[66:81]
	s_waitcnt lgkmcnt(5)
	v_mfma_f32_32x32x16_bf16 v[82:97], v[230:233], v[98:101], 0
	s_waitcnt lgkmcnt(4)
	v_mfma_f32_32x32x16_bf16 v[82:97], v[234:237], v[102:105], v[82:97]
	s_waitcnt lgkmcnt(3)
	v_mfma_f32_32x32x16_bf16 v[66:81], v[238:241], v[106:109], v[66:81]
	s_waitcnt lgkmcnt(2)
	v_mfma_f32_32x32x16_bf16 v[82:97], v[242:245], v[106:109], v[82:97]
	s_waitcnt lgkmcnt(1)
	v_mfma_f32_32x32x16_bf16 v[66:81], v[246:249], v[110:113], v[66:81]
	s_waitcnt lgkmcnt(0)
	v_mfma_f32_32x32x16_bf16 v[82:97], v[250:253], v[110:113], v[82:97]
	s_cbranch_scc1 .LBB0_837
	v_add_u32_e32 v122, s78, v162
	v_add_u32_e32 v123, 64, v122
	v_cmp_gt_u32_e32 vcc, s96, v123
	v_cmp_gt_u32_e64 s[42:43], s72, v123
	v_add_u32_e32 v123, 0x41, v122
	v_cmp_gt_u32_e64 s[12:13], s96, v123
	v_cmp_gt_u32_e64 s[44:45], s72, v123
	v_add_u32_e32 v123, 0x42, v122
	v_cmp_gt_u32_e64 s[14:15], s96, v123
	v_cmp_gt_u32_e64 s[46:47], s72, v123
	v_add_u32_e32 v123, 0x43, v122
	v_cmp_gt_u32_e64 s[16:17], s96, v123
	v_cmp_gt_u32_e64 s[48:49], s72, v123
	v_add_u32_e32 v123, 0x48, v122
	v_cmp_gt_u32_e64 s[18:19], s96, v123
	v_cmp_gt_u32_e64 s[50:51], s72, v123
	v_add_u32_e32 v123, 0x49, v122
	v_cmp_gt_u32_e64 s[20:21], s96, v123
	v_cmp_gt_u32_e64 s[52:53], s72, v123
	v_add_u32_e32 v123, 0x4a, v122
	v_cmp_gt_u32_e64 s[22:23], s96, v123
	v_cmp_gt_u32_e64 s[54:55], s72, v123
	v_add_u32_e32 v123, 0x4b, v122
	v_cmp_gt_u32_e64 s[24:25], s96, v123
	v_cmp_gt_u32_e64 s[56:57], s72, v123
	v_add_u32_e32 v123, 0x50, v122
	v_cmp_gt_u32_e64 s[26:27], s96, v123
	v_cmp_gt_u32_e64 s[58:59], s72, v123
	v_add_u32_e32 v123, 0x51, v122
	v_cmp_gt_u32_e64 s[28:29], s96, v123
	v_cmp_gt_u32_e64 s[60:61], s72, v123
	v_add_u32_e32 v123, 0x52, v122
	v_cmp_gt_u32_e64 s[30:31], s96, v123
	v_cmp_gt_u32_e64 s[62:63], s72, v123
	v_add_u32_e32 v123, 0x53, v122
	v_cmp_gt_u32_e64 s[34:35], s96, v123
	v_cmp_gt_u32_e64 s[64:65], s72, v123
	v_add_u32_e32 v123, 0x58, v122
	v_cmp_gt_u32_e64 s[36:37], s96, v123
	v_cmp_gt_u32_e64 s[66:67], s72, v123
	v_add_u32_e32 v123, 0x59, v122
	v_cmp_gt_u32_e64 s[38:39], s96, v123
	v_cmp_gt_u32_e64 s[68:69], s72, v123
	v_add_u32_e32 v123, 0x5a, v122
	v_cmp_gt_u32_e64 s[70:71], s72, v123
	s_or_b64 s[68:69], s[70:71], s[68:69]
	s_or_b64 s[66:67], s[68:69], s[66:67]
	s_or_b64 s[64:65], s[66:67], s[64:65]
	s_or_b64 s[62:63], s[64:65], s[62:63]
	s_or_b64 s[60:61], s[62:63], s[60:61]
	s_or_b64 s[58:59], s[60:61], s[58:59]
	s_or_b64 s[56:57], s[58:59], s[56:57]
	s_or_b64 s[54:55], s[56:57], s[54:55]
	s_or_b64 s[52:53], s[54:55], s[52:53]
	s_or_b64 s[50:51], s[52:53], s[50:51]
	s_or_b64 s[48:49], s[50:51], s[48:49]
	s_or_b64 s[46:47], s[48:49], s[46:47]
	s_or_b64 s[44:45], s[46:47], s[44:45]
	s_or_b64 s[42:43], s[44:45], s[42:43]
	v_add_u32_e32 v122, 0x5b, v122
	v_cmp_gt_u32_e64 s[40:41], s96, v123
	v_cndmask_b32_e64 v96, v184, v96, s[70:71]
	v_cndmask_b32_e64 v95, v184, v95, s[68:69]
	v_cndmask_b32_e64 v94, v184, v94, s[66:67]
	v_cndmask_b32_e64 v93, v184, v93, s[64:65]
	v_cndmask_b32_e64 v92, v184, v92, s[62:63]
	v_cndmask_b32_e64 v91, v184, v91, s[60:61]
	v_cndmask_b32_e64 v90, v184, v90, s[58:59]
	v_cndmask_b32_e64 v89, v184, v89, s[56:57]
	v_cndmask_b32_e64 v88, v184, v88, s[54:55]
	v_cndmask_b32_e64 v87, v184, v87, s[52:53]
	v_cndmask_b32_e64 v86, v184, v86, s[50:51]
	v_cndmask_b32_e64 v85, v184, v85, s[48:49]
	v_cndmask_b32_e64 v84, v184, v84, s[46:47]
	v_cndmask_b32_e64 v83, v184, v83, s[44:45]
	v_cndmask_b32_e64 v82, v184, v82, s[42:43]
	v_cmp_gt_u32_e64 s[42:43], s96, v122
	v_cmp_le_u32_e64 s[44:45], s72, v122
	s_and_saveexec_b64 s[6:7], s[44:45]
	s_mov_b32 s44, 0xf149f2ca
	v_mov_b32_e32 v97, s44
	s_or_b64 exec, exec, s[6:7]
	s_or_b64 s[40:41], s[42:43], s[40:41]
	s_or_b64 s[38:39], s[40:41], s[38:39]
	s_or_b64 s[36:37], s[38:39], s[36:37]
	s_or_b64 s[34:35], s[36:37], s[34:35]
	s_or_b64 s[30:31], s[34:35], s[30:31]
	s_or_b64 s[28:29], s[30:31], s[28:29]
	s_or_b64 s[26:27], s[28:29], s[26:27]
	s_or_b64 s[24:25], s[26:27], s[24:25]
	s_or_b64 s[22:23], s[24:25], s[22:23]
	s_or_b64 s[20:21], s[22:23], s[20:21]
	s_or_b64 s[18:19], s[20:21], s[18:19]
	s_or_b64 s[16:17], s[18:19], s[16:17]
	s_or_b64 s[14:15], s[16:17], s[14:15]
	s_or_b64 s[12:13], s[14:15], s[12:13]
	s_or_b64 vcc, s[12:13], vcc
	v_cndmask_b32_e64 v80, v184, v80, s[40:41]
	v_cndmask_b32_e64 v79, v184, v79, s[38:39]
	v_cndmask_b32_e64 v78, v184, v78, s[36:37]
	v_cndmask_b32_e64 v77, v184, v77, s[34:35]
	v_cndmask_b32_e64 v76, v184, v76, s[30:31]
	v_cndmask_b32_e64 v75, v184, v75, s[28:29]
	v_cndmask_b32_e64 v74, v184, v74, s[26:27]
	v_cndmask_b32_e64 v73, v184, v73, s[24:25]
	v_cndmask_b32_e64 v72, v184, v72, s[22:23]
	v_cndmask_b32_e64 v71, v184, v71, s[20:21]
	v_cndmask_b32_e64 v70, v184, v70, s[18:19]
	v_cndmask_b32_e64 v69, v184, v69, s[16:17]
	v_cndmask_b32_e64 v68, v184, v68, s[14:15]
	v_cndmask_b32_e64 v67, v184, v67, s[12:13]
	v_cndmask_b32_e32 v66, v184, v66, vcc
	v_cndmask_b32_e64 v81, v184, v81, s[42:43]
	s_movk_i32 s65, 0x600
	s_mov_b64 s[66:67], 0x80
	s_mov_b64 s[68:69], 0x1e90c900

; __device__ __forceinline__ int crow(int r, int hi) { return (r & 3) + 8 * (r >> 2) + 4 * hi; }
; template <int DQK>
; __device__ __forceinline__ void qkt(f32x16& p0, f32x16& p1, const bf16* Ks, const bf16x8* qr, int r32, int hi, int k0, int L) {
;   p0 = f32x16{}; p1 = f32x16{};
; #pragma unroll
;   for (int d0 = 0; d0 < DQK / 16; ++d0) { int cb = (d0 * 16 + hi * 8) * 2;
;     bf16x8 b0 = *reinterpret_cast<const bf16x8*>((const char*)Ks + KSWZ(r32, cb));
;     bf16x8 b1 = *reinterpret_cast<const bf16x8*>((const char*)Ks + KSWZ(32 + r32, cb));
;     p0 = __builtin_amdgcn_mfma_f32_32x32x16_bf16(b0, qr[d0], p0, 0, 0, 0);
;     p1 = __builtin_amdgcn_mfma_f32_32x32x16_bf16(b1, qr[d0], p1, 0, 0, 0); }
;   if (k0 + KVBLK > L) {
; #pragma unroll
;     for (int r = 0; r < 16; ++r) { const int key = k0 + crow(r, hi);
;       if (key >= L) p0[r] = -1e30f;
;       if (key + 32 >= L) p1[r] = -1e30f; }
;   }
.LBB0_842:
	s_or_b64 exec, exec, s[2:3]
	s_barrier
	s_waitcnt vmcnt(2)
	s_waitcnt vmcnt(2)
	ds_write_b128 v160, v[114:117]
	ds_write_b128 v161, v[118:121] offset:32768
	s_waitcnt lgkmcnt(0)
	s_barrier
	s_and_saveexec_b64 s[2:3], s[8:9]
	s_cbranch_execz .LBB0_848
	ds_read_b128 v[222:225], v167 offset:32768
	ds_read_b128 v[226:229], v168 offset:32768
	ds_read_b128 v[230:233], v167 offset:40960
	ds_read_b128 v[234:237], v168 offset:40960
	ds_read_b128 v[238:241], v169 offset:32768
	ds_read_b128 v[242:245], v169 offset:40960
	ds_read_b128 v[246:249], v171 offset:32768
	ds_read_b128 v[250:253], v171 offset:40960
	s_add_i32 s6, s78, 0x80
	s_cmp_le_u32 s6, s79
	s_waitcnt lgkmcnt(7)
	v_mfma_f32_32x32x16_bf16 v[50:65], v[222:225], v[98:101], 0
	s_waitcnt lgkmcnt(6)
	v_mfma_f32_32x32x16_bf16 v[50:65], v[226:229], v[102:105], v[50:65]
	s_waitcnt lgkmcnt(5)
	v_mfma_f32_32x32x16_bf16 v[34:49], v[230:233], v[98:101], 0
	s_waitcnt lgkmcnt(4)
	v_mfma_f32_32x32x16_bf16 v[34:49], v[234:237], v[102:105], v[34:49]
	s_waitcnt lgkmcnt(3)
	v_mfma_f32_32x32x16_bf16 v[50:65], v[238:241], v[106:109], v[50:65]
	s_waitcnt lgkmcnt(2)
	v_mfma_f32_32x32x16_bf16 v[34:49], v[242:245], v[106:109], v[34:49]
	s_waitcnt lgkmcnt(1)
	v_mfma_f32_32x32x16_bf16 v[50:65], v[246:249], v[110:113], v[50:65]
	s_waitcnt lgkmcnt(0)
	v_mfma_f32_32x32x16_bf16 v[34:49], v[250:253], v[110:113], v[34:49]
	s_cbranch_scc1 .LBB0_847
	v_add_u32_e32 v130, s78, v162
	v_add_u32_e32 v131, 0x80, v130
	v_cmp_gt_u32_e32 vcc, s96, v131
	v_cmp_gt_u32_e64 s[42:43], s72, v131
	v_add_u32_e32 v131, 0x81, v130
	v_cmp_gt_u32_e64 s[12:13], s96, v131
	v_cmp_gt_u32_e64 s[44:45], s72, v131
	v_add_u32_e32 v131, 0x82, v130
	v_cmp_gt_u32_e64 s[14:15], s96, v131
	v_cmp_gt_u32_e64 s[46:47], s72, v131
	v_add_u32_e32 v131, 0x83, v130
	v_cmp_gt_u32_e64 s[16:17], s96, v131
	v_cmp_gt_u32_e64 s[48:49], s72, v131
	v_add_u32_e32 v131, 0x88, v130
	v_cmp_gt_u32_e64 s[18:19], s96, v131
	v_cmp_gt_u32_e64 s[50:51], s72, v131
	v_add_u32_e32 v131, 0x89, v130
	v_cmp_gt_u32_e64 s[20:21], s96, v131
	v_cmp_gt_u32_e64 s[52:53], s72, v131
	v_add_u32_e32 v131, 0x8a, v130
	v_cmp_gt_u32_e64 s[22:23], s96, v131
	v_cmp_gt_u32_e64 s[54:55], s72, v131
	v_add_u32_e32 v131, 0x8b, v130
	v_cmp_gt_u32_e64 s[24:25], s96, v131
	v_cmp_gt_u32_e64 s[56:57], s72, v131
	v_add_u32_e32 v131, 0x90, v130
	v_cmp_gt_u32_e64 s[26:27], s96, v131
	v_cmp_gt_u32_e64 s[58:59], s72, v131
	v_add_u32_e32 v131, 0x91, v130
	v_cmp_gt_u32_e64 s[28:29], s96, v131
	v_cmp_gt_u32_e64 s[60:61], s72, v131
	v_add_u32_e32 v131, 0x92, v130
	v_cmp_gt_u32_e64 s[30:31], s96, v131
	v_cmp_gt_u32_e64 s[62:63], s72, v131
	v_add_u32_e32 v131, 0x93, v130
	v_cmp_gt_u32_e64 s[34:35], s96, v131
	v_cmp_gt_u32_e64 s[64:65], s72, v131
	v_add_u32_e32 v131, 0x98, v130
	v_cmp_gt_u32_e64 s[36:37], s96, v131
	v_cmp_gt_u32_e64 s[66:67], s72, v131
	v_add_u32_e32 v131, 0x99, v130
	v_cmp_gt_u32_e64 s[38:39], s96, v131
	v_cmp_gt_u32_e64 s[68:69], s72, v131
	v_add_u32_e32 v131, 0x9a, v130
	v_cmp_gt_u32_e64 s[70:71], s72, v131
	s_or_b64 s[68:69], s[70:71], s[68:69]
	s_or_b64 s[66:67], s[68:69], s[66:67]
	s_or_b64 s[64:65], s[66:67], s[64:65]
	s_or_b64 s[62:63], s[64:65], s[62:63]
	s_or_b64 s[60:61], s[62:63], s[60:61]
	s_or_b64 s[58:59], s[60:61], s[58:59]
	s_or_b64 s[56:57], s[58:59], s[56:57]
	s_or_b64 s[54:55], s[56:57], s[54:55]
	s_or_b64 s[52:53], s[54:55], s[52:53]
	s_or_b64 s[50:51], s[52:53], s[50:51]
	s_or_b64 s[48:49], s[50:51], s[48:49]
	s_or_b64 s[46:47], s[48:49], s[46:47]
	s_or_b64 s[44:45], s[46:47], s[44:45]
	s_or_b64 s[42:43], s[44:45], s[42:43]
	v_add_u32_e32 v130, 0x9b, v130
	v_cmp_gt_u32_e64 s[40:41], s96, v131
	v_cndmask_b32_e64 v48, v184, v48, s[70:71]
	v_cndmask_b32_e64 v47, v184, v47, s[68:69]
	v_cndmask_b32_e64 v46, v184, v46, s[66:67]
	v_cndmask_b32_e64 v45, v184, v45, s[64:65]
	v_cndmask_b32_e64 v44, v184, v44, s[62:63]
	v_cndmask_b32_e64 v43, v184, v43, s[60:61]
	v_cndmask_b32_e64 v42, v184, v42, s[58:59]
	v_cndmask_b32_e64 v41, v184, v41, s[56:57]
	v_cndmask_b32_e64 v40, v184, v40, s[54:55]
	v_cndmask_b32_e64 v39, v184, v39, s[52:53]
	v_cndmask_b32_e64 v38, v184, v38, s[50:51]
	v_cndmask_b32_e64 v37, v184, v37, s[48:49]
	v_cndmask_b32_e64 v36, v184, v36, s[46:47]
	v_cndmask_b32_e64 v35, v184, v35, s[44:45]
	v_cndmask_b32_e64 v34, v184, v34, s[42:43]
	v_cmp_gt_u32_e64 s[42:43], s96, v130
	v_cmp_le_u32_e64 s[44:45], s72, v130
	s_and_saveexec_b64 s[6:7], s[44:45]
	s_mov_b32 s44, 0xf149f2ca
	v_mov_b32_e32 v49, s44
	s_or_b64 exec, exec, s[6:7]
	s_or_b64 s[40:41], s[42:43], s[40:41]
	s_or_b64 s[38:39], s[40:41], s[38:39]
	s_or_b64 s[36:37], s[38:39], s[36:37]
	s_or_b64 s[34:35], s[36:37], s[34:35]
	s_or_b64 s[30:31], s[34:35], s[30:31]
	s_or_b64 s[28:29], s[30:31], s[28:29]
	s_or_b64 s[26:27], s[28:29], s[26:27]
	s_or_b64 s[24:25], s[26:27], s[24:25]
	s_or_b64 s[22:23], s[24:25], s[22:23]
	s_or_b64 s[20:21], s[22:23], s[20:21]
	s_or_b64 s[18:19], s[20:21], s[18:19]
	s_or_b64 s[16:17], s[18:19], s[16:17]
	s_or_b64 s[14:15], s[16:17], s[14:15]
	s_or_b64 s[12:13], s[14:15], s[12:13]
	s_or_b64 vcc, s[12:13], vcc
	v_cndmask_b32_e64 v64, v184, v64, s[40:41]
	v_cndmask_b32_e64 v63, v184, v63, s[38:39]
	v_cndmask_b32_e64 v62, v184, v62, s[36:37]
	v_cndmask_b32_e64 v61, v184, v61, s[34:35]
	v_cndmask_b32_e64 v60, v184, v60, s[30:31]
	v_cndmask_b32_e64 v59, v184, v59, s[28:29]
	v_cndmask_b32_e64 v58, v184, v58, s[26:27]
	v_cndmask_b32_e64 v57, v184, v57, s[24:25]
	v_cndmask_b32_e64 v56, v184, v56, s[22:23]
	v_cndmask_b32_e64 v55, v184, v55, s[20:21]
	v_cndmask_b32_e64 v54, v184, v54, s[18:19]
	v_cndmask_b32_e64 v53, v184, v53, s[16:17]
	v_cndmask_b32_e64 v52, v184, v52, s[14:15]
	v_cndmask_b32_e64 v51, v184, v51, s[12:13]
	v_cndmask_b32_e32 v50, v184, v50, vcc
	v_cndmask_b32_e64 v65, v184, v65, s[42:43]
	s_movk_i32 s65, 0x600
	s_mov_b64 s[66:67], 0x80
	s_mov_b64 s[68:69], 0x1e90c900

; __device__ __forceinline__ int crow(int r, int hi) { return (r & 3) + 8 * (r >> 2) + 4 * hi; }
; template <int DQK>
; __device__ __forceinline__ void qkt(f32x16& p0, f32x16& p1, const bf16* Ks, const bf16x8* qr, int r32, int hi, int k0, int L) {
;   p0 = f32x16{}; p1 = f32x16{};
; #pragma unroll
;   for (int d0 = 0; d0 < DQK / 16; ++d0) { int cb = (d0 * 16 + hi * 8) * 2;
;     bf16x8 b0 = *reinterpret_cast<const bf16x8*>((const char*)Ks + KSWZ(r32, cb));
;     bf16x8 b1 = *reinterpret_cast<const bf16x8*>((const char*)Ks + KSWZ(32 + r32, cb));
;     p0 = __builtin_amdgcn_mfma_f32_32x32x16_bf16(b0, qr[d0], p0, 0, 0, 0);
;     p1 = __builtin_amdgcn_mfma_f32_32x32x16_bf16(b1, qr[d0], p1, 0, 0, 0); }
;   if (k0 + KVBLK > L) {
; #pragma unroll
;     for (int r = 0; r < 16; ++r) { const int key = k0 + crow(r, hi);
;       if (key >= L) p0[r] = -1e30f;
;       if (key + 32 >= L) p1[r] = -1e30f; }
;   }
.LBB0_883:
	s_and_saveexec_b64 s[2:3], s[10:11]
	s_cbranch_execz .LBB0_889
	ds_read_b128 v[222:225], v200 offset:49152
	ds_read_b128 v[226:229], v200 offset:57344
	ds_read_b128 v[230:233], v201 offset:49152
	ds_read_b128 v[234:237], v201 offset:57344
	ds_read_b128 v[238:241], v202 offset:49152
	ds_read_b128 v[242:245], v202 offset:57344
	ds_read_b128 v[246:249], v203 offset:49152
	ds_read_b128 v[250:253], v203 offset:57344
	s_add_i32 s14, s4, 64
	s_cmp_le_u32 s14, s5
	s_waitcnt lgkmcnt(7)
	v_mfma_f32_32x32x16_bf16 v[80:95], v[222:225], v[112:115], 0
	ds_read_b128 v[222:225], v204 offset:49152
	s_waitcnt lgkmcnt(7)
	v_mfma_f32_32x32x16_bf16 v[96:111], v[226:229], v[112:115], 0
	ds_read_b128 v[226:229], v204 offset:57344
	s_waitcnt lgkmcnt(7)
	v_mfma_f32_32x32x16_bf16 v[80:95], v[230:233], v[116:119], v[80:95]
	ds_read_b128 v[230:233], v205 offset:49152
	s_waitcnt lgkmcnt(7)
	v_mfma_f32_32x32x16_bf16 v[96:111], v[234:237], v[116:119], v[96:111]
	ds_read_b128 v[234:237], v205 offset:57344
	s_waitcnt lgkmcnt(7)
	v_mfma_f32_32x32x16_bf16 v[80:95], v[238:241], v[120:123], v[80:95]
	s_waitcnt lgkmcnt(6)
	v_mfma_f32_32x32x16_bf16 v[96:111], v[242:245], v[120:123], v[96:111]
	s_waitcnt lgkmcnt(5)
	v_mfma_f32_32x32x16_bf16 v[80:95], v[246:249], v[124:127], v[80:95]
	s_waitcnt lgkmcnt(4)
	v_mfma_f32_32x32x16_bf16 v[96:111], v[250:253], v[124:127], v[96:111]
	s_waitcnt lgkmcnt(3)
	v_mfma_f32_32x32x16_bf16 v[80:95], v[222:225], v[128:131], v[80:95]
	s_waitcnt lgkmcnt(2)
	v_mfma_f32_32x32x16_bf16 v[96:111], v[226:229], v[128:131], v[96:111]
	s_waitcnt lgkmcnt(1)
	v_mfma_f32_32x32x16_bf16 v[80:95], v[230:233], v[132:135], v[80:95]
	s_waitcnt lgkmcnt(0)
	v_mfma_f32_32x32x16_bf16 v[96:111], v[234:237], v[132:135], v[96:111]
	s_cbranch_scc1 .LBB0_888
	v_add_u32_e32 v0, s4, v196
	v_add_u32_e32 v2, 64, v0
	v_cmp_gt_u32_e32 vcc, s96, v2
	v_cmp_gt_u32_e64 s[44:45], s78, v2
	v_add_u32_e32 v2, 0x41, v0
	v_cmp_gt_u32_e64 s[14:15], s96, v2
	v_cmp_gt_u32_e64 s[46:47], s78, v2
	v_add_u32_e32 v2, 0x42, v0
	v_cmp_gt_u32_e64 s[16:17], s96, v2
	v_cmp_gt_u32_e64 s[48:49], s78, v2
	v_add_u32_e32 v2, 0x43, v0
	v_cmp_gt_u32_e64 s[18:19], s96, v2
	v_cmp_gt_u32_e64 s[50:51], s78, v2
	v_add_u32_e32 v2, 0x48, v0
	v_cmp_gt_u32_e64 s[20:21], s96, v2
	v_cmp_gt_u32_e64 s[52:53], s78, v2
	v_add_u32_e32 v2, 0x49, v0
	v_cmp_gt_u32_e64 s[22:23], s96, v2
	v_cmp_gt_u32_e64 s[54:55], s78, v2
	v_add_u32_e32 v2, 0x4a, v0
	v_cmp_gt_u32_e64 s[24:25], s96, v2
	v_cmp_gt_u32_e64 s[56:57], s78, v2
	v_add_u32_e32 v2, 0x4b, v0
	v_cmp_gt_u32_e64 s[26:27], s96, v2
	v_cmp_gt_u32_e64 s[58:59], s78, v2
	v_add_u32_e32 v2, 0x50, v0
	v_cmp_gt_u32_e64 s[28:29], s96, v2
	v_cmp_gt_u32_e64 s[60:61], s78, v2
	v_add_u32_e32 v2, 0x51, v0
	v_cmp_gt_u32_e64 s[30:31], s96, v2
	v_cmp_gt_u32_e64 s[62:63], s78, v2
	v_add_u32_e32 v2, 0x52, v0
	v_cmp_gt_u32_e64 s[34:35], s96, v2
	v_cmp_gt_u32_e64 s[64:65], s78, v2
	v_add_u32_e32 v2, 0x53, v0
	v_cmp_gt_u32_e64 s[36:37], s96, v2
	v_cmp_gt_u32_e64 s[66:67], s78, v2
	v_add_u32_e32 v2, 0x58, v0
	v_cmp_gt_u32_e64 s[38:39], s96, v2
	v_cmp_gt_u32_e64 s[68:69], s78, v2
	v_add_u32_e32 v2, 0x59, v0
	v_cmp_gt_u32_e64 s[40:41], s96, v2
	v_cmp_gt_u32_e64 s[70:71], s78, v2
	v_add_u32_e32 v2, 0x5a, v0
	v_cmp_gt_u32_e64 s[72:73], s78, v2
	s_or_b64 s[70:71], s[72:73], s[70:71]
	s_or_b64 s[68:69], s[70:71], s[68:69]
	s_or_b64 s[66:67], s[68:69], s[66:67]
	s_or_b64 s[64:65], s[66:67], s[64:65]
	s_or_b64 s[62:63], s[64:65], s[62:63]
	s_or_b64 s[60:61], s[62:63], s[60:61]
	s_or_b64 s[58:59], s[60:61], s[58:59]
	s_or_b64 s[56:57], s[58:59], s[56:57]
	s_or_b64 s[54:55], s[56:57], s[54:55]
	s_or_b64 s[52:53], s[54:55], s[52:53]
	s_or_b64 s[50:51], s[52:53], s[50:51]
	s_or_b64 s[48:49], s[50:51], s[48:49]
	s_or_b64 s[46:47], s[48:49], s[46:47]
	s_or_b64 s[44:45], s[46:47], s[44:45]
	v_add_u32_e32 v0, 0x5b, v0
	v_cmp_gt_u32_e64 s[42:43], s96, v2
	v_cndmask_b32_e64 v110, v184, v110, s[72:73]
	v_cndmask_b32_e64 v109, v184, v109, s[70:71]
	v_cndmask_b32_e64 v108, v184, v108, s[68:69]
	v_cndmask_b32_e64 v107, v184, v107, s[66:67]
	v_cndmask_b32_e64 v106, v184, v106, s[64:65]
	v_cndmask_b32_e64 v105, v184, v105, s[62:63]
	v_cndmask_b32_e64 v104, v184, v104, s[60:61]
	v_cndmask_b32_e64 v103, v184, v103, s[58:59]
	v_cndmask_b32_e64 v102, v184, v102, s[56:57]
	v_cndmask_b32_e64 v101, v184, v101, s[54:55]
	v_cndmask_b32_e64 v100, v184, v100, s[52:53]
	v_cndmask_b32_e64 v99, v184, v99, s[50:51]
	v_cndmask_b32_e64 v98, v184, v98, s[48:49]
	v_cndmask_b32_e64 v97, v184, v97, s[46:47]
	v_cndmask_b32_e64 v96, v184, v96, s[44:45]
	v_cmp_gt_u32_e64 s[44:45], s96, v0
	v_cmp_le_u32_e64 s[46:47], s78, v0
	s_and_saveexec_b64 s[48:49], s[46:47]
	s_mov_b32 s46, 0xf149f2ca
	v_mov_b32_e32 v111, s46
	s_or_b64 exec, exec, s[48:49]
	s_or_b64 s[42:43], s[44:45], s[42:43]
	s_or_b64 s[40:41], s[42:43], s[40:41]
	s_or_b64 s[38:39], s[40:41], s[38:39]
	s_or_b64 s[36:37], s[38:39], s[36:37]
	s_or_b64 s[34:35], s[36:37], s[34:35]
	s_or_b64 s[30:31], s[34:35], s[30:31]
	s_or_b64 s[28:29], s[30:31], s[28:29]
	s_or_b64 s[26:27], s[28:29], s[26:27]
	s_or_b64 s[24:25], s[26:27], s[24:25]
	s_or_b64 s[22:23], s[24:25], s[22:23]
	s_or_b64 s[20:21], s[22:23], s[20:21]
	s_or_b64 s[18:19], s[20:21], s[18:19]
	s_or_b64 s[16:17], s[18:19], s[16:17]
	s_or_b64 s[14:15], s[16:17], s[14:15]
	s_or_b64 vcc, s[14:15], vcc
	v_cndmask_b32_e64 v94, v184, v94, s[42:43]
	v_cndmask_b32_e64 v93, v184, v93, s[40:41]
	v_cndmask_b32_e64 v92, v184, v92, s[38:39]
	v_cndmask_b32_e64 v91, v184, v91, s[36:37]
	v_cndmask_b32_e64 v90, v184, v90, s[34:35]
	v_cndmask_b32_e64 v89, v184, v89, s[30:31]
	v_cndmask_b32_e64 v88, v184, v88, s[28:29]
	v_cndmask_b32_e64 v87, v184, v87, s[26:27]
	v_cndmask_b32_e64 v86, v184, v86, s[24:25]
	v_cndmask_b32_e64 v85, v184, v85, s[22:23]
	v_cndmask_b32_e64 v84, v184, v84, s[20:21]
	v_cndmask_b32_e64 v83, v184, v83, s[18:19]
	v_cndmask_b32_e64 v82, v184, v82, s[16:17]
	v_cndmask_b32_e64 v81, v184, v81, s[14:15]
	v_cndmask_b32_e32 v80, v184, v80, vcc
	v_cndmask_b32_e64 v95, v184, v95, s[44:45]
	s_movk_i32 s65, 0x600
	s_mov_b64 s[66:67], 0x80
	s_mov_b64 s[68:69], 0x1e90c900

; __device__ __forceinline__ int crow(int r, int hi) { return (r & 3) + 8 * (r >> 2) + 4 * hi; }
; template <int DQK>
; __device__ __forceinline__ void qkt(f32x16& p0, f32x16& p1, const bf16* Ks, const bf16x8* qr, int r32, int hi, int k0, int L) {
;   p0 = f32x16{}; p1 = f32x16{};
; #pragma unroll
;   for (int d0 = 0; d0 < DQK / 16; ++d0) { int cb = (d0 * 16 + hi * 8) * 2;
;     bf16x8 b0 = *reinterpret_cast<const bf16x8*>((const char*)Ks + KSWZ(r32, cb));
;     bf16x8 b1 = *reinterpret_cast<const bf16x8*>((const char*)Ks + KSWZ(32 + r32, cb));
;     p0 = __builtin_amdgcn_mfma_f32_32x32x16_bf16(b0, qr[d0], p0, 0, 0, 0);
;     p1 = __builtin_amdgcn_mfma_f32_32x32x16_bf16(b1, qr[d0], p1, 0, 0, 0); }
;   if (k0 + KVBLK > L) {
; #pragma unroll
;     for (int r = 0; r < 16; ++r) { const int key = k0 + crow(r, hi);
;       if (key >= L) p0[r] = -1e30f;
;       if (key + 32 >= L) p1[r] = -1e30f; }
;   }
.LBB0_895:
	s_or_b64 exec, exec, s[2:3]
	s_barrier
	s_waitcnt vmcnt(2)
	s_waitcnt vmcnt(3)
	ds_write_b128 v193, v[144:147]
	s_waitcnt vmcnt(2)
	ds_write_b128 v194, v[148:151] offset:32768
	s_and_saveexec_b64 s[2:3], s[8:9]
	ds_write_b128 v195, v[136:139] offset:32768
	s_or_b64 exec, exec, s[2:3]
	s_waitcnt lgkmcnt(0)
	s_barrier
	s_and_saveexec_b64 s[2:3], s[10:11]
	s_cbranch_execz .LBB0_903
	ds_read_b128 v[222:225], v200 offset:32768
	ds_read_b128 v[226:229], v200 offset:40960
	ds_read_b128 v[230:233], v201 offset:32768
	ds_read_b128 v[234:237], v201 offset:40960
	ds_read_b128 v[238:241], v202 offset:32768
	ds_read_b128 v[242:245], v202 offset:40960
	ds_read_b128 v[246:249], v203 offset:32768
	ds_read_b128 v[250:253], v203 offset:40960
	s_add_i32 s14, s4, 0x80
	s_cmp_le_u32 s14, s5
	s_waitcnt lgkmcnt(7)
	v_mfma_f32_32x32x16_bf16 v[64:79], v[222:225], v[112:115], 0
	ds_read_b128 v[222:225], v204 offset:32768
	s_waitcnt lgkmcnt(7)
	v_mfma_f32_32x32x16_bf16 v[48:63], v[226:229], v[112:115], 0
	ds_read_b128 v[226:229], v204 offset:40960
	s_waitcnt lgkmcnt(7)
	v_mfma_f32_32x32x16_bf16 v[64:79], v[230:233], v[116:119], v[64:79]
	ds_read_b128 v[230:233], v205 offset:32768
	s_waitcnt lgkmcnt(7)
	v_mfma_f32_32x32x16_bf16 v[48:63], v[234:237], v[116:119], v[48:63]
	ds_read_b128 v[234:237], v205 offset:40960
	s_waitcnt lgkmcnt(7)
	v_mfma_f32_32x32x16_bf16 v[64:79], v[238:241], v[120:123], v[64:79]
	s_waitcnt lgkmcnt(6)
	v_mfma_f32_32x32x16_bf16 v[48:63], v[242:245], v[120:123], v[48:63]
	s_waitcnt lgkmcnt(5)
	v_mfma_f32_32x32x16_bf16 v[64:79], v[246:249], v[124:127], v[64:79]
	s_waitcnt lgkmcnt(4)
	v_mfma_f32_32x32x16_bf16 v[48:63], v[250:253], v[124:127], v[48:63]
	s_waitcnt lgkmcnt(3)
	v_mfma_f32_32x32x16_bf16 v[64:79], v[222:225], v[128:131], v[64:79]
	s_waitcnt lgkmcnt(2)
	v_mfma_f32_32x32x16_bf16 v[48:63], v[226:229], v[128:131], v[48:63]
	s_waitcnt lgkmcnt(1)
	v_mfma_f32_32x32x16_bf16 v[64:79], v[230:233], v[132:135], v[64:79]
	s_waitcnt lgkmcnt(0)
	v_mfma_f32_32x32x16_bf16 v[48:63], v[234:237], v[132:135], v[48:63]
	s_cbranch_scc1 .LBB0_902
	v_add_u32_e32 v0, s4, v196
	v_add_u32_e32 v10, 0x80, v0
	v_cmp_gt_u32_e32 vcc, s96, v10
	v_cmp_gt_u32_e64 s[44:45], s78, v10
	v_add_u32_e32 v10, 0x81, v0
	v_cmp_gt_u32_e64 s[14:15], s96, v10
	v_cmp_gt_u32_e64 s[46:47], s78, v10
	v_add_u32_e32 v10, 0x82, v0
	v_cmp_gt_u32_e64 s[16:17], s96, v10
	v_cmp_gt_u32_e64 s[48:49], s78, v10
	v_add_u32_e32 v10, 0x83, v0
	v_cmp_gt_u32_e64 s[18:19], s96, v10
	v_cmp_gt_u32_e64 s[50:51], s78, v10
	v_add_u32_e32 v10, 0x88, v0
	v_cmp_gt_u32_e64 s[20:21], s96, v10
	v_cmp_gt_u32_e64 s[52:53], s78, v10
	v_add_u32_e32 v10, 0x89, v0
	v_cmp_gt_u32_e64 s[22:23], s96, v10
	v_cmp_gt_u32_e64 s[54:55], s78, v10
	v_add_u32_e32 v10, 0x8a, v0
	v_cmp_gt_u32_e64 s[24:25], s96, v10
	v_cmp_gt_u32_e64 s[56:57], s78, v10
	v_add_u32_e32 v10, 0x8b, v0
	v_cmp_gt_u32_e64 s[26:27], s96, v10
	v_cmp_gt_u32_e64 s[58:59], s78, v10
	v_add_u32_e32 v10, 0x90, v0
	v_cmp_gt_u32_e64 s[28:29], s96, v10
	v_cmp_gt_u32_e64 s[60:61], s78, v10
	v_add_u32_e32 v10, 0x91, v0
	v_cmp_gt_u32_e64 s[30:31], s96, v10
	v_cmp_gt_u32_e64 s[62:63], s78, v10
	v_add_u32_e32 v10, 0x92, v0
	v_cmp_gt_u32_e64 s[34:35], s96, v10
	v_cmp_gt_u32_e64 s[64:65], s78, v10
	v_add_u32_e32 v10, 0x93, v0
	v_cmp_gt_u32_e64 s[36:37], s96, v10
	v_cmp_gt_u32_e64 s[66:67], s78, v10
	v_add_u32_e32 v10, 0x98, v0
	v_cmp_gt_u32_e64 s[38:39], s96, v10
	v_cmp_gt_u32_e64 s[68:69], s78, v10
	v_add_u32_e32 v10, 0x99, v0
	v_cmp_gt_u32_e64 s[40:41], s96, v10
	v_cmp_gt_u32_e64 s[70:71], s78, v10
	v_add_u32_e32 v10, 0x9a, v0
	v_cmp_gt_u32_e64 s[72:73], s78, v10
	s_or_b64 s[70:71], s[72:73], s[70:71]
	s_or_b64 s[68:69], s[70:71], s[68:69]
	s_or_b64 s[66:67], s[68:69], s[66:67]
	s_or_b64 s[64:65], s[66:67], s[64:65]
	s_or_b64 s[62:63], s[64:65], s[62:63]
	s_or_b64 s[60:61], s[62:63], s[60:61]
	s_or_b64 s[58:59], s[60:61], s[58:59]
	s_or_b64 s[56:57], s[58:59], s[56:57]
	s_or_b64 s[54:55], s[56:57], s[54:55]
	s_or_b64 s[52:53], s[54:55], s[52:53]
	s_or_b64 s[50:51], s[52:53], s[50:51]
	s_or_b64 s[48:49], s[50:51], s[48:49]
	s_or_b64 s[46:47], s[48:49], s[46:47]
	s_or_b64 s[44:45], s[46:47], s[44:45]
	v_add_u32_e32 v0, 0x9b, v0
	v_cmp_gt_u32_e64 s[42:43], s96, v10
	v_cndmask_b32_e64 v62, v184, v62, s[72:73]
	v_cndmask_b32_e64 v61, v184, v61, s[70:71]
	v_cndmask_b32_e64 v60, v184, v60, s[68:69]
	v_cndmask_b32_e64 v59, v184, v59, s[66:67]
	v_cndmask_b32_e64 v58, v184, v58, s[64:65]
	v_cndmask_b32_e64 v57, v184, v57, s[62:63]
	v_cndmask_b32_e64 v56, v184, v56, s[60:61]
	v_cndmask_b32_e64 v55, v184, v55, s[58:59]
	v_cndmask_b32_e64 v54, v184, v54, s[56:57]
	v_cndmask_b32_e64 v53, v184, v53, s[54:55]
	v_cndmask_b32_e64 v52, v184, v52, s[52:53]
	v_cndmask_b32_e64 v51, v184, v51, s[50:51]
	v_cndmask_b32_e64 v50, v184, v50, s[48:49]
	v_cndmask_b32_e64 v49, v184, v49, s[46:47]
	v_cndmask_b32_e64 v48, v184, v48, s[44:45]
	v_cmp_gt_u32_e64 s[44:45], s96, v0
	v_cmp_le_u32_e64 s[46:47], s78, v0
	s_and_saveexec_b64 s[48:49], s[46:47]
	s_mov_b32 s46, 0xf149f2ca
	v_mov_b32_e32 v63, s46
	s_or_b64 exec, exec, s[48:49]
	s_or_b64 s[42:43], s[44:45], s[42:43]
	s_or_b64 s[40:41], s[42:43], s[40:41]
	s_or_b64 s[38:39], s[40:41], s[38:39]
	s_or_b64 s[36:37], s[38:39], s[36:37]
	s_or_b64 s[34:35], s[36:37], s[34:35]
	s_or_b64 s[30:31], s[34:35], s[30:31]
	s_or_b64 s[28:29], s[30:31], s[28:29]
	s_or_b64 s[26:27], s[28:29], s[26:27]
	s_or_b64 s[24:25], s[26:27], s[24:25]
	s_or_b64 s[22:23], s[24:25], s[22:23]
	s_or_b64 s[20:21], s[22:23], s[20:21]
	s_or_b64 s[18:19], s[20:21], s[18:19]
	s_or_b64 s[16:17], s[18:19], s[16:17]
	s_or_b64 s[14:15], s[16:17], s[14:15]
	s_or_b64 vcc, s[14:15], vcc
	v_cndmask_b32_e64 v78, v184, v78, s[42:43]
	v_cndmask_b32_e64 v77, v184, v77, s[40:41]
	v_cndmask_b32_e64 v76, v184, v76, s[38:39]
	v_cndmask_b32_e64 v75, v184, v75, s[36:37]
	v_cndmask_b32_e64 v74, v184, v74, s[34:35]
	v_cndmask_b32_e64 v73, v184, v73, s[30:31]
	v_cndmask_b32_e64 v72, v184, v72, s[28:29]
	v_cndmask_b32_e64 v71, v184, v71, s[26:27]
	v_cndmask_b32_e64 v70, v184, v70, s[24:25]
	v_cndmask_b32_e64 v69, v184, v69, s[22:23]
	v_cndmask_b32_e64 v68, v184, v68, s[20:21]
	v_cndmask_b32_e64 v67, v184, v67, s[18:19]
	v_cndmask_b32_e64 v66, v184, v66, s[16:17]
	v_cndmask_b32_e64 v65, v184, v65, s[14:15]
	v_cndmask_b32_e32 v64, v184, v64, vcc
	v_cndmask_b32_e64 v79, v184, v79, s[44:45]
	s_movk_i32 s65, 0x600
	s_mov_b64 s[66:67], 0x80
	s_mov_b64 s[68:69], 0x1e90c900
